# nt policy on the prep job's once-read u row loads
# baseline (speedup 1.0000x reference)
.LBB0_301:
	v_mul_hi_i32 v0, v17, s76
	v_lshrrev_b32_e32 v1, 31, v0
	v_add_u32_e32 v2, v0, v1
	s_movk_i32 s0, 0xffe8
	v_mad_u64_u32 v[0:1], s[0:1], v2, s0, v[22:23]
	v_cmp_lt_i32_e64 s[8:9], 11, v0
	v_mul_lo_u32 v45, v2, 24
	v_readlane_b32 s60, v254, 12
	v_cndmask_b32_e64 v29, 0, -12, s[8:9]
	v_sub_u32_e32 v0, v29, v45
	v_readlane_b32 s66, v254, 18
	v_readlane_b32 s67, v254, 19
	v_add_u32_e32 v46, s24, v2
	v_add_u32_e32 v28, v22, v0
	v_mov_b64_e32 v[0:1], s[66:67]
	v_mad_i64_i32 v[2:3], s[0:1], v46, s77, v[0:1]
	v_cndmask_b32_e64 v112, v123, v124, s[8:9]
	v_lshlrev_b32_e32 v4, 7, v28
	v_lshl_add_u64 v[2:3], v[2:3], 0, v[112:113]
	v_ashrrev_i32_e32 v5, 31, v4
	v_lshl_add_u64 v[2:3], v[4:5], 1, v[2:3]
	v_lshlrev_b32_e32 v112, 1, v16
	v_lshl_add_u64 v[2:3], v[2:3], 0, v[112:113]
	global_load_dwordx4 v[12:15], v[2:3], off nt
	v_add_u32_e32 v2, 8, v17
	v_mul_hi_i32 v3, v2, s76
	v_lshrrev_b32_e32 v4, 31, v3
	v_add_u32_e32 v3, v3, v4
	v_mul_lo_u32 v4, v3, 6
	v_sub_u32_e32 v2, v2, v4
	v_lshl_or_b32 v2, v2, 2, v23
	v_cmp_lt_i32_e64 s[6:7], 11, v2
	v_add_u32_e32 v44, s24, v3
	v_mov_b32_e32 v5, v113
	v_cndmask_b32_e64 v3, 0, -12, s[6:7]
	v_add_u32_e32 v43, v3, v2
	v_mad_i64_i32 v[2:3], s[0:1], v44, s77, v[0:1]
	v_cndmask_b32_e64 v4, v123, v124, s[6:7]
	v_lshl_add_u64 v[2:3], v[2:3], 0, v[4:5]
	v_lshlrev_b32_e32 v4, 7, v43
	v_ashrrev_i32_e32 v5, 31, v4
	v_lshl_add_u64 v[2:3], v[4:5], 1, v[2:3]
	v_lshl_add_u64 v[2:3], v[2:3], 0, v[112:113]
	global_load_dwordx4 v[4:7], v[2:3], off nt
	v_add_u32_e32 v2, 16, v17
	v_mul_hi_i32 v3, v2, s76
	v_lshrrev_b32_e32 v8, 31, v3
	v_add_u32_e32 v3, v3, v8
	v_mul_lo_u32 v8, v3, 6
	v_sub_u32_e32 v2, v2, v8
	v_lshl_or_b32 v2, v2, 2, v23
	v_cmp_lt_i32_e64 s[4:5], 11, v2
	v_add_u32_e32 v42, s24, v3
	v_mad_i64_i32 v[0:1], s[0:1], v42, s77, v[0:1]
	v_cndmask_b32_e64 v3, 0, -12, s[4:5]
	v_add_u32_e32 v41, v3, v2
	v_cndmask_b32_e64 v2, v123, v124, s[4:5]
	v_mov_b32_e32 v3, v113
	v_lshl_add_u64 v[0:1], v[0:1], 0, v[2:3]
	v_lshlrev_b32_e32 v2, 7, v41
	v_ashrrev_i32_e32 v3, 31, v2
	v_lshl_add_u64 v[0:1], v[2:3], 1, v[0:1]
	v_lshl_add_u64 v[0:1], v[0:1], 0, v[112:113]
	global_load_dwordx4 v[0:3], v[0:1], off nt
	v_cmp_gt_i32_e64 s[10:11], 10, v28
	v_cmp_gt_i32_e64 s[12:13], 8, v28
	v_cmp_lt_i32_e64 s[14:15], 7, v28
	s_and_b64 s[0:1], s[8:9], s[10:11]
	v_readlane_b32 s61, v254, 13
	v_readlane_b32 s62, v254, 14
	v_readlane_b32 s63, v254, 15
	v_readlane_b32 s64, v254, 16
	v_readlane_b32 s65, v254, 17
	v_readlane_b32 s68, v254, 20
	v_readlane_b32 s69, v254, 21
	v_readlane_b32 s70, v254, 22
	v_readlane_b32 s71, v254, 23
	v_readlane_b32 s72, v254, 24
	v_readlane_b32 s73, v254, 25
	v_readlane_b32 s74, v254, 26
	v_readlane_b32 s75, v254, 27
	v_lshlrev_b32_e32 v210, 2, v16
	v_mov_b32_e32 v211, 0
	v_cmp_gt_i32_e64 s[98:99], 8, v28
	v_mov_b32_e32 v206, s20
	v_mov_b32_e32 v207, s2
	v_mov_b32_e32 v208, s21
	v_mov_b32_e32 v209, s3
	v_cndmask_b32_e64 v206, v207, v206, s[98:99]
	v_cndmask_b32_e64 v207, v209, v208, s[98:99]
	v_lshl_add_u64 v[206:207], v[206:207], 0, v[210:211]
	global_load_dwordx4 v[130:133], v[206:207], off
	global_load_dwordx4 v[134:137], v[206:207], off offset:16
	s_cbranch_vccz .Lprepa_norope0
	v_and_b32_e32 v208, s55, v46
	v_lshlrev_b32_e32 v208, 9, v208
	v_mov_b32_e32 v209, 0
	v_lshl_add_u64 v[208:209], v[20:21], 0, v[208:209]
	global_load_dwordx4 v[138:141], v[208:209], off offset:48
	global_load_dwordx4 v[142:145], v[208:209], off offset:32
	global_load_dwordx4 v[146:149], v[208:209], off offset:16
	global_load_dwordx4 v[150:153], v[208:209], off

.LBB0_1011:
	v_mul_hi_i32 v0, v17, s66
	v_lshrrev_b32_e32 v1, 31, v0
	v_add_u32_e32 v2, v0, v1
	s_movk_i32 s0, 0xffe8
	v_mad_u64_u32 v[0:1], s[0:1], v2, s0, v[22:23]
	v_cmp_lt_i32_e64 s[8:9], 11, v0
	v_mul_lo_u32 v46, v2, 24
	v_readlane_b32 s68, v254, 12
	v_cndmask_b32_e64 v29, 0, -12, s[8:9]
	v_sub_u32_e32 v0, v29, v46
	v_readlane_b32 s74, v254, 18
	v_readlane_b32 s75, v254, 19
	v_add_u32_e32 v47, s52, v2
	v_add_u32_e32 v28, v22, v0
	v_mov_b64_e32 v[0:1], s[74:75]
	v_mad_i64_i32 v[2:3], s[0:1], v47, s97, v[0:1]
	v_cndmask_b32_e64 v112, v123, v124, s[8:9]
	v_lshlrev_b32_e32 v4, 7, v28
	v_lshl_add_u64 v[2:3], v[2:3], 0, v[112:113]
	v_ashrrev_i32_e32 v5, 31, v4
	v_lshl_add_u64 v[2:3], v[4:5], 1, v[2:3]
	v_lshlrev_b32_e32 v112, 1, v16
	v_lshl_add_u64 v[2:3], v[2:3], 0, v[112:113]
	global_load_dwordx4 v[12:15], v[2:3], off nt
	v_add_u32_e32 v2, 8, v17
	v_mul_hi_i32 v3, v2, s66
	v_lshrrev_b32_e32 v4, 31, v3
	v_add_u32_e32 v3, v3, v4
	v_mul_lo_u32 v4, v3, 6
	v_sub_u32_e32 v2, v2, v4
	v_lshl_or_b32 v2, v2, 2, v23
	v_cmp_lt_i32_e64 s[6:7], 11, v2
	v_add_u32_e32 v45, s52, v3
	v_mov_b32_e32 v5, v113
	v_cndmask_b32_e64 v3, 0, -12, s[6:7]
	v_add_u32_e32 v44, v3, v2
	v_mad_i64_i32 v[2:3], s[0:1], v45, s97, v[0:1]
	v_cndmask_b32_e64 v4, v123, v124, s[6:7]
	v_lshl_add_u64 v[2:3], v[2:3], 0, v[4:5]
	v_lshlrev_b32_e32 v4, 7, v44
	v_ashrrev_i32_e32 v5, 31, v4
	v_lshl_add_u64 v[2:3], v[4:5], 1, v[2:3]
	v_lshl_add_u64 v[2:3], v[2:3], 0, v[112:113]
	global_load_dwordx4 v[4:7], v[2:3], off nt
	v_add_u32_e32 v2, 16, v17
	v_mul_hi_i32 v3, v2, s66
	v_lshrrev_b32_e32 v8, 31, v3
	v_add_u32_e32 v3, v3, v8
	v_mul_lo_u32 v8, v3, 6
	v_sub_u32_e32 v2, v2, v8
	v_lshl_or_b32 v2, v2, 2, v23
	v_cmp_lt_i32_e64 s[4:5], 11, v2
	v_add_u32_e32 v43, s52, v3
	v_mad_i64_i32 v[0:1], s[0:1], v43, s97, v[0:1]
	v_cndmask_b32_e64 v3, 0, -12, s[4:5]
	v_add_u32_e32 v42, v3, v2
	v_cndmask_b32_e64 v2, v123, v124, s[4:5]
	v_mov_b32_e32 v3, v113
	v_lshl_add_u64 v[0:1], v[0:1], 0, v[2:3]
	v_lshlrev_b32_e32 v2, 7, v42
	v_ashrrev_i32_e32 v3, 31, v2
	v_lshl_add_u64 v[0:1], v[2:3], 1, v[0:1]
	v_lshl_add_u64 v[0:1], v[0:1], 0, v[112:113]
	global_load_dwordx4 v[0:3], v[0:1], off nt
	v_cmp_gt_i32_e64 s[10:11], 10, v28
	v_cmp_gt_i32_e64 s[12:13], 8, v28
	v_cmp_lt_i32_e64 s[14:15], 7, v28
	s_and_b64 s[0:1], s[8:9], s[10:11]
	v_readlane_b32 s69, v254, 13
	v_readlane_b32 s70, v254, 14
	v_readlane_b32 s71, v254, 15
	v_readlane_b32 s72, v254, 16
	v_readlane_b32 s73, v254, 17
	v_readlane_b32 s76, v254, 20
	v_readlane_b32 s77, v254, 21
	v_readlane_b32 s78, v254, 22
	v_readlane_b32 s79, v254, 23
	v_readlane_b32 s80, v254, 24
	v_readlane_b32 s81, v254, 25
	v_readlane_b32 s82, v254, 26
	v_readlane_b32 s83, v254, 27
	v_lshlrev_b32_e32 v210, 2, v16
	v_mov_b32_e32 v211, 0
	v_cmp_gt_i32_e64 s[98:99], 8, v28
	v_mov_b32_e32 v206, s34
	v_mov_b32_e32 v207, s2
	v_mov_b32_e32 v208, s35
	v_mov_b32_e32 v209, s3
	v_cndmask_b32_e64 v206, v207, v206, s[98:99]
	v_cndmask_b32_e64 v207, v209, v208, s[98:99]
	v_lshl_add_u64 v[206:207], v[206:207], 0, v[210:211]
	global_load_dwordx4 v[130:133], v[206:207], off offset:512
	global_load_dwordx4 v[134:137], v[206:207], off offset:528
	s_cbranch_vccz .Lprepb_norope0
	v_and_b32_e32 v208, s56, v47
	v_lshlrev_b32_e32 v208, 9, v208
	v_mov_b32_e32 v209, 0
	v_lshl_add_u64 v[208:209], v[20:21], 0, v[208:209]
	global_load_dwordx4 v[138:141], v[208:209], off offset:48
	global_load_dwordx4 v[142:145], v[208:209], off offset:32
	global_load_dwordx4 v[146:149], v[208:209], off offset:16
	global_load_dwordx4 v[150:153], v[208:209], off
